# v64 + O4 MLA suffix attention: K/V tile prefetch distance 2 via a second staging register set (top part per parity, shared arithmetic)
# speedup vs baseline: 1.0052x; 1.0052x over previous
.LBB0_569:
	s_or_b64 exec, exec, s[0:1]
	v_add_u32_e32 v32, v153, v136
	s_waitcnt vmcnt(0)
	ds_write_b128 v32, v[208:211] offset:35840
	s_waitcnt lgkmcnt(0)
	s_barrier
	v_add_u32_e32 v96, v128, v154
	ds_read_b128 v[32:35], v96 offset:13312
	ds_read_b128 v[88:91], v96 offset:13344
	s_mov_b32 s0, 0xff61b1e6
	s_waitcnt lgkmcnt(1)
	v_mfma_f32_32x32x16_bf16 v[48:63], v[32:35], v[84:87], 0
	ds_read_b128 v[32:35], v96 offset:19968
	ds_read_b128 v[92:95], v96 offset:20000
	s_waitcnt lgkmcnt(1)
	v_mfma_f32_32x32x16_bf16 v[32:47], v[32:35], v[84:87], 0
	v_mfma_f32_32x32x16_bf16 v[48:63], v[88:91], v[80:83], v[48:63]
	s_waitcnt lgkmcnt(0)
	v_mfma_f32_32x32x16_bf16 v[32:47], v[92:95], v[80:83], v[32:47]
	ds_read_b128 v[80:83], v96 offset:13376
	ds_read_b128 v[84:87], v96 offset:13408
	s_waitcnt lgkmcnt(1)
	v_mfma_f32_32x32x16_bf16 v[48:63], v[80:83], v[76:79], v[48:63]
	ds_read_b128 v[80:83], v96 offset:20032
	ds_read_b128 v[88:91], v96 offset:20064
	s_waitcnt lgkmcnt(1)
	v_mfma_f32_32x32x16_bf16 v[32:47], v[80:83], v[76:79], v[32:47]
	v_mfma_f32_32x32x16_bf16 v[48:63], v[84:87], v[72:75], v[48:63]
	s_waitcnt lgkmcnt(0)
	v_mfma_f32_32x32x16_bf16 v[32:47], v[88:91], v[72:75], v[32:47]
	ds_read_b128 v[72:75], v96 offset:13440
	ds_read_b128 v[76:79], v96 offset:13472
	ds_read_b128 v[104:107], v96 offset:20096
	ds_read_b128 v[108:111], v96 offset:20128
	s_waitcnt lgkmcnt(3)
	v_mfma_f32_32x32x16_bf16 v[48:63], v[72:75], v[68:71], v[48:63]
	v_sub_u32_e32 v72, v128, v137
	v_add_u32_e32 v72, v72, v151
	v_add_u32_e32 v73, 0x8800, v72
	v_add_u32_e32 v72, 0x9800, v72
	ds_read2_b64 v[100:103], v73 offset0:128 offset1:130
	ds_read2_b64 v[92:95], v73 offset0:132 offset1:134
	s_waitcnt lgkmcnt(4)
	v_mfma_f32_32x32x16_bf16 v[48:63], v[76:79], v[64:67], v[48:63]
	ds_read2_b64 v[96:99], v72 offset0:192 offset1:194
	ds_read2_b64 v[88:91], v72 offset0:196 offset1:198
	ds_read2_b64 v[84:87], v73 offset0:136 offset1:138
	ds_read2_b64 v[80:83], v72 offset0:200 offset1:202
	ds_read2_b64 v[76:79], v73 offset0:140 offset1:142
	ds_read2_b64 v[72:75], v72 offset0:204 offset1:206
	s_nop 5
	v_max3_f32 v112, v48, s0, v49
	s_waitcnt lgkmcnt(9)
	v_mfma_f32_32x32x16_bf16 v[32:47], v[104:107], v[68:71], v[32:47]
	v_max3_f32 v68, v112, v50, v51
	v_max3_f32 v68, v68, v52, v53
	v_max3_f32 v68, v68, v54, v55
	v_max3_f32 v68, v68, v56, v57
	v_max3_f32 v68, v68, v58, v59
	v_max3_f32 v68, v68, v60, v61
	v_max3_f32 v68, v68, v62, v63
	s_waitcnt lgkmcnt(8)
	v_mfma_f32_32x32x16_bf16 v[32:47], v[108:111], v[64:67], v[32:47]
	s_mov_b32 s0, 0x41000000
	s_nop 10
	v_max3_f32 v64, v68, v32, v33
	v_max3_f32 v64, v64, v34, v35
	v_max3_f32 v64, v64, v36, v37
	v_max3_f32 v64, v64, v38, v39
	v_max3_f32 v64, v64, v40, v41
	v_max3_f32 v64, v64, v42, v43
	v_max3_f32 v64, v64, v44, v45
	v_max3_f32 v64, v64, v46, v47
	v_mul_f32_e32 v64, 0x3e16c740, v64
	v_mov_b32_e32 v65, v64
	s_nop 1
	v_permlane32_swap_b32_e32 v64, v65
	v_max3_f32 v64, v185, v64, v65
	v_sub_f32_e32 v65, v64, v185
	v_cmp_lt_f32_e32 vcc, s0, v65
	s_cbranch_vccz .LBB0_599
	v_sub_f32_e32 v65, v185, v64
	v_exp_f32_e32 v66, v65
	v_xor_b32_e32 v64, 0x80000000, v64
	v_pk_mul_f32 v[30:31], v[30:31], v[66:67] op_sel_hi:[1,0]
	v_pk_mul_f32 v[28:29], v[28:29], v[66:67] op_sel_hi:[1,0]
	v_pk_mul_f32 v[26:27], v[26:27], v[66:67] op_sel_hi:[1,0]
	v_pk_mul_f32 v[24:25], v[24:25], v[66:67] op_sel_hi:[1,0]
	v_pk_mul_f32 v[22:23], v[22:23], v[66:67] op_sel_hi:[1,0]
	v_pk_mul_f32 v[20:21], v[20:21], v[66:67] op_sel_hi:[1,0]
	v_pk_mul_f32 v[18:19], v[18:19], v[66:67] op_sel_hi:[1,0]
	v_pk_mul_f32 v[16:17], v[16:17], v[66:67] op_sel_hi:[1,0]
	v_pk_mul_f32 v[14:15], v[14:15], v[66:67] op_sel_hi:[1,0]
	v_pk_mul_f32 v[12:13], v[12:13], v[66:67] op_sel_hi:[1,0]
	v_pk_mul_f32 v[10:11], v[10:11], v[66:67] op_sel_hi:[1,0]
	v_pk_mul_f32 v[8:9], v[8:9], v[66:67] op_sel_hi:[1,0]
	v_pk_mul_f32 v[6:7], v[6:7], v[66:67] op_sel_hi:[1,0]
	v_pk_mul_f32 v[4:5], v[4:5], v[66:67] op_sel_hi:[1,0]
	v_pk_mul_f32 v[2:3], v[2:3], v[66:67] op_sel_hi:[1,0]
	v_pk_mul_f32 v[0:1], v[0:1], v[66:67] op_sel_hi:[1,0]
	v_mul_f32_e32 v152, v152, v66

.LBB0_609:
	s_or_b64 exec, exec, s[6:7]
	s_ashr_i32 s3, s2, 31
	s_mul_hi_i32 s5, s16, 0x28000
	s_mul_i32 s16, s16, 0x28000
	s_add_u32 s4, s28, s16
	s_addc_u32 s5, s29, s5
	v_ashrrev_i32_e32 v9, 3, v4
	v_mov_b64_e32 v[10:11], s[4:5]
	s_movk_i32 s6, 0xa00
	v_lshlrev_b32_e32 v12, 4, v4
	v_mad_i64_i32 v[10:11], s[4:5], v9, s6, v[10:11]
	v_and_b32_e32 v136, 0x70, v12
	v_mov_b32_e32 v137, v129
	v_lshl_add_u64 v[10:11], v[10:11], 0, v[136:137]
	global_load_dwordx4 v[96:99], v[10:11], off
	v_mad_i64_i32 v[10:11], s[4:5], v9, s6, 0
	v_add_u32_e32 v6, v6, v5
	s_movk_i32 s4, 0xc0
	v_mad_i64_i32 v[12:13], s[4:5], v6, s4, 0
	v_mul_lo_u32 v5, v6, 12
	s_movk_i32 s4, 0xd0
	s_add_i32 s20, s20, s12
	v_mul_lo_u32 v153, v9, s80
	v_sub_u32_e32 v9, v4, v5
	v_mul_lo_u32 v183, v6, s4
	v_mul_lo_u32 v181, v7, s4
	v_mad_i64_i32 v[6:7], s[4:5], s20, v174, v[10:11]
	v_and_b32_e32 v14, 31, v4
	v_lshlrev_b32_e32 v4, 3, v9
	v_or_b32_e32 v6, v6, v136
	v_ashrrev_i32_e32 v5, 31, v4
	v_lshl_add_u64 v[144:145], s[42:43], 0, v[6:7]
	v_mad_i64_i32 v[6:7], s[4:5], s20, v175, v[12:13]
	v_mad_i64_i32 v[2:3], s[4:5], s20, v175, v[2:3]
	v_mul_u32_u24_e32 v154, 0xd0, v14
	v_mul_u32_u24_e32 v151, 0x90, v14
	v_lshl_add_u64 v[4:5], v[4:5], 1, v[6:7]
	v_lshl_add_u64 v[0:1], v[0:1], 1, v[2:3]
	v_mov_b32_e32 v14, v129
	v_mov_b32_e32 v15, v129
	v_lshlrev_b32_e32 v184, 4, v9
	v_lshlrev_b32_e32 v182, 4, v8
	v_lshl_add_u64 v[146:147], s[50:51], 0, v[4:5]
	v_lshl_add_u64 v[148:149], s[50:51], 0, v[0:1]
	v_mov_b32_e32 v0, v129
	v_mov_b32_e32 v1, v129
	v_mov_b32_e32 v2, v129
	v_mov_b32_e32 v3, v129
	v_mov_b32_e32 v4, v129
	v_mov_b32_e32 v5, v129
	v_mov_b32_e32 v6, v129
	v_mov_b32_e32 v7, v129
	v_mov_b32_e32 v8, v129
	v_mov_b32_e32 v9, v129
	v_mov_b32_e32 v10, v129
	v_mov_b32_e32 v11, v129
	v_mov_b32_e32 v12, v129
	v_mov_b32_e32 v13, v129
	v_mov_b64_e32 v[30:31], v[14:15]
	v_ashrrev_i32_e32 v135, 31, v134
	v_lshlrev_b32_e32 v137, 3, v150
	s_mov_b32 s6, 0
	v_mov_b32_e32 v152, 0
	v_mov_b32_e32 v186, 0xff61b1e6
	v_mov_b64_e32 v[28:29], v[12:13]
	v_mov_b64_e32 v[26:27], v[10:11]
	v_mov_b64_e32 v[24:25], v[8:9]
	v_mov_b64_e32 v[22:23], v[6:7]
	v_mov_b64_e32 v[20:21], v[4:5]
	v_mov_b64_e32 v[18:19], v[2:3]
	v_mov_b64_e32 v[16:17], v[0:1]
	s_and_saveexec_b64 s[4:5], s[0:1]
	s_cbranch_execz .Lo4p_1
	global_load_dwordx4 v[200:203], v[146:147], off
.Lo4p_1:
	s_or_b64 exec, exec, s[4:5]
	s_and_saveexec_b64 s[4:5], s[36:37]
	s_cbranch_execz .Lo4p_2
	global_load_dwordx4 v[204:207], v[148:149], off
.Lo4p_2:
	s_or_b64 exec, exec, s[4:5]
	global_load_dwordx4 v[208:211], v[144:145], off
	s_mov_b64 s[4:5], 0x3000
	v_lshl_add_u64 v[146:147], v[146:147], 0, s[4:5]
	v_lshl_add_u64 v[148:149], v[148:149], 0, s[4:5]
	s_mov_b64 s[4:5], 0x80
	v_lshl_add_u64 v[144:145], v[144:145], 0, s[4:5]
	s_and_b32 s7, s6, 1
	s_mul_i32 s16, s7, 0x3400
	s_and_saveexec_b64 s[4:5], s[0:1]
	s_cbranch_execz .LBB0_612
	s_branch .LBB0_611
.Lo4B_top:
	s_and_saveexec_b64 s[4:5], s[0:1]
	s_cbranch_execz .Lo4B_612
.Lo4B_611:
	v_add3_u32 v32, s16, v183, v184
	s_waitcnt vmcnt(3)
	ds_write_b128 v32, v[200:203]
.Lo4B_612:
	s_or_b64 exec, exec, s[4:5]
	s_and_saveexec_b64 s[4:5], s[36:37]
	s_cbranch_execz .Lo4B_614
	v_add3_u32 v32, s16, v181, v182
	s_waitcnt vmcnt(3)
	ds_write_b128 v32, v[204:207]
.Lo4B_614:
	s_or_b64 exec, exec, s[4:5]
	s_lshl_b32 s4, s7, 12
	s_sub_i32 s7, s16, s4
	v_add3_u32 v32, s7, v153, v136
	s_waitcnt vmcnt(2)
	ds_write_b128 v32, v[208:211] offset:26624
	s_waitcnt lgkmcnt(0)
	s_barrier
	s_cmp_ge_u32 s6, 18
	s_cbranch_scc1 .Lo4B_noload
	s_and_saveexec_b64 s[4:5], s[0:1]
	s_cbranch_execz .Lo4B_616
	global_load_dwordx4 v[200:203], v[146:147], off

.Lo4B_618:
	s_or_b64 exec, exec, s[4:5]
	global_load_dwordx4 v[208:211], v[144:145], off

.LBB0_610:
	v_mov_b32_e32 v186, v185
	s_and_b32 s7, s6, 1
	s_mul_i32 s16, s7, 0x3400
	s_cmp_lg_u32 s7, 0
	s_cbranch_scc1 .Lo4B_top
	s_and_saveexec_b64 s[4:5], s[0:1]
	s_cbranch_execz .LBB0_612
.LBB0_611:
	v_add3_u32 v32, s16, v183, v184
	s_waitcnt vmcnt(3)
	ds_write_b128 v32, v[88:91]
.LBB0_612:
	s_or_b64 exec, exec, s[4:5]
	s_and_saveexec_b64 s[4:5], s[36:37]
	s_cbranch_execz .LBB0_614
	v_add3_u32 v32, s16, v181, v182
	s_waitcnt vmcnt(3)
	ds_write_b128 v32, v[92:95]
.LBB0_614:
	s_or_b64 exec, exec, s[4:5]
	s_lshl_b32 s4, s7, 12
	s_sub_i32 s7, s16, s4
	v_add3_u32 v32, s7, v153, v136
	s_waitcnt vmcnt(2)
	ds_write_b128 v32, v[96:99] offset:26624
	s_waitcnt lgkmcnt(0)
	s_barrier
	s_cmp_ge_u32 s6, 18
	s_cbranch_scc1 .Lo4A_noload
	s_and_saveexec_b64 s[4:5], s[0:1]
	s_cbranch_execz .LBB0_616
	global_load_dwordx4 v[88:91], v[146:147], off

.Lo4A_noload:
.Lo4_compute:
	v_add3_u32 v112, s16, v128, v154
	ds_read_b128 v[32:35], v112
	ds_read_b128 v[100:103], v112 offset:32
	s_mov_b32 s4, 0xff61b1e6
	s_waitcnt lgkmcnt(1)
	v_mfma_f32_32x32x16_bf16 v[48:63], v[32:35], v[84:87], 0
	ds_read_b128 v[32:35], v112 offset:6656
	ds_read_b128 v[104:107], v112 offset:6688
	s_waitcnt lgkmcnt(1)
	v_mfma_f32_32x32x16_bf16 v[32:47], v[32:35], v[84:87], 0
	v_mfma_f32_32x32x16_bf16 v[48:63], v[100:103], v[80:83], v[48:63]
	s_waitcnt lgkmcnt(0)
	v_mfma_f32_32x32x16_bf16 v[32:47], v[104:107], v[80:83], v[32:47]
	ds_read_b128 v[100:103], v112 offset:64
	ds_read_b128 v[104:107], v112 offset:96
	s_waitcnt lgkmcnt(1)
	v_mfma_f32_32x32x16_bf16 v[48:63], v[100:103], v[76:79], v[48:63]
	ds_read_b128 v[100:103], v112 offset:6720
	ds_read_b128 v[108:111], v112 offset:6752
	s_waitcnt lgkmcnt(1)
	v_mfma_f32_32x32x16_bf16 v[32:47], v[100:103], v[76:79], v[32:47]
	v_mfma_f32_32x32x16_bf16 v[48:63], v[104:107], v[72:75], v[48:63]
	ds_read_b128 v[100:103], v112 offset:128
	ds_read_b128 v[104:107], v112 offset:160
	ds_read_b128 v[188:191], v112 offset:6784
	ds_read_b128 v[192:195], v112 offset:6816
	s_waitcnt lgkmcnt(4)
	v_mfma_f32_32x32x16_bf16 v[32:47], v[108:111], v[72:75], v[32:47]
	s_waitcnt lgkmcnt(3)
	v_mfma_f32_32x32x16_bf16 v[48:63], v[100:103], v[68:71], v[48:63]
	v_add3_u32 v100, s7, v137, v151
	v_add_u32_e32 v101, 0x6800, v100
	v_add_u32_e32 v100, 0x7800, v100
	ds_read2_b64 v[130:133], v101 offset1:2
	ds_read2_b64 v[120:123], v101 offset0:4 offset1:6
	s_waitcnt lgkmcnt(4)
	v_mfma_f32_32x32x16_bf16 v[48:63], v[104:107], v[64:67], v[48:63]
	ds_read2_b64 v[124:127], v100 offset0:64 offset1:66
	ds_read2_b64 v[116:119], v100 offset0:68 offset1:70
	ds_read2_b64 v[112:115], v101 offset0:8 offset1:10
	ds_read2_b64 v[108:111], v100 offset0:72 offset1:74
	ds_read2_b64 v[104:107], v101 offset0:12 offset1:14
	ds_read2_b64 v[100:103], v100 offset0:76 offset1:78
	s_nop 5
	v_max3_f32 v185, v48, s4, v49
	s_waitcnt lgkmcnt(9)
	v_mfma_f32_32x32x16_bf16 v[32:47], v[188:191], v[68:71], v[32:47]
	v_max3_f32 v185, v185, v50, v51
	v_max3_f32 v185, v185, v52, v53
	v_max3_f32 v185, v185, v54, v55
	v_max3_f32 v185, v185, v56, v57
	v_max3_f32 v185, v185, v58, v59
	v_max3_f32 v185, v185, v60, v61
	v_max3_f32 v185, v185, v62, v63
	s_waitcnt lgkmcnt(8)
	v_mfma_f32_32x32x16_bf16 v[32:47], v[192:195], v[64:67], v[32:47]
	s_mov_b32 s4, 0x41000000
	s_nop 10
	v_max3_f32 v185, v185, v32, v33
	v_max3_f32 v185, v185, v34, v35
	v_max3_f32 v185, v185, v36, v37
	v_max3_f32 v185, v185, v38, v39
	v_max3_f32 v185, v185, v40, v41
	v_max3_f32 v185, v185, v42, v43
	v_max3_f32 v185, v185, v44, v45
	v_max3_f32 v185, v185, v46, v47
	v_mul_f32_e32 v185, 0x3e16c740, v185
	v_mov_b32_e32 v187, v185
	s_nop 1
	v_permlane32_swap_b32_e32 v185, v187
	v_max3_f32 v185, v186, v185, v187
	v_sub_f32_e32 v187, v185, v186
	v_cmp_lt_f32_e32 vcc, s4, v187
	s_cbranch_vccz .LBB0_620
	v_sub_f32_e32 v186, v186, v185
	v_exp_f32_e32 v186, v186
	s_nop 0
	v_pk_mul_f32 v[30:31], v[30:31], v[186:187] op_sel_hi:[1,0]
	v_pk_mul_f32 v[28:29], v[28:29], v[186:187] op_sel_hi:[1,0]
	v_pk_mul_f32 v[26:27], v[26:27], v[186:187] op_sel_hi:[1,0]
	v_pk_mul_f32 v[24:25], v[24:25], v[186:187] op_sel_hi:[1,0]
	v_pk_mul_f32 v[22:23], v[22:23], v[186:187] op_sel_hi:[1,0]
	v_pk_mul_f32 v[20:21], v[20:21], v[186:187] op_sel_hi:[1,0]
	v_pk_mul_f32 v[18:19], v[18:19], v[186:187] op_sel_hi:[1,0]
	v_pk_mul_f32 v[16:17], v[16:17], v[186:187] op_sel_hi:[1,0]
	v_pk_mul_f32 v[14:15], v[14:15], v[186:187] op_sel_hi:[1,0]
	v_pk_mul_f32 v[12:13], v[12:13], v[186:187] op_sel_hi:[1,0]
	v_pk_mul_f32 v[10:11], v[10:11], v[186:187] op_sel_hi:[1,0]
	v_pk_mul_f32 v[8:9], v[8:9], v[186:187] op_sel_hi:[1,0]
	v_pk_mul_f32 v[6:7], v[6:7], v[186:187] op_sel_hi:[1,0]
	v_pk_mul_f32 v[4:5], v[4:5], v[186:187] op_sel_hi:[1,0]
	v_pk_mul_f32 v[2:3], v[2:3], v[186:187] op_sel_hi:[1,0]
	v_pk_mul_f32 v[0:1], v[0:1], v[186:187] op_sel_hi:[1,0]
	v_mul_f32_e32 v152, v152, v186
	s_branch .LBB0_621

.LBB0_621:
	v_fma_f32 v48, v48, s96, -v185
	v_exp_f32_e32 v48, v48
	v_fma_f32 v49, v49, s96, -v185
	v_exp_f32_e32 v49, v49
	v_fma_f32 v50, v50, s96, -v185
	v_exp_f32_e32 v50, v50
	v_fma_f32 v51, v51, s96, -v185
	v_fma_f32 v52, v52, s96, -v185
	v_fma_f32 v53, v53, s96, -v185
	v_fma_f32 v54, v54, s96, -v185
	v_fma_f32 v55, v55, s96, -v185
	v_exp_f32_e32 v51, v51
	v_exp_f32_e32 v52, v52
	v_exp_f32_e32 v53, v53
	v_exp_f32_e32 v54, v54
	v_exp_f32_e32 v55, v55
	v_add_f32_e32 v152, v152, v48
	v_add_f32_e32 v152, v49, v152
	v_add_f32_e32 v152, v50, v152
	v_add_f32_e32 v152, v51, v152
	v_cvt_pk_bf16_f32 v48, v48, v49
	v_cvt_pk_bf16_f32 v49, v50, v51
	v_cvt_pk_bf16_f32 v50, v52, v53
	v_cvt_pk_bf16_f32 v51, v54, v55
	v_fma_f32 v32, v32, s96, -v185
	v_fma_f32 v56, v56, s96, -v185
	s_waitcnt lgkmcnt(7)
	v_mfma_f32_32x32x16_bf16 v[16:31], v[130:133], v[48:51], v[16:31]
	v_fma_f32 v57, v57, s96, -v185
	v_fma_f32 v58, v58, s96, -v185
	v_fma_f32 v59, v59, s96, -v185
	v_fma_f32 v60, v60, s96, -v185
	v_fma_f32 v61, v61, s96, -v185
	v_fma_f32 v62, v62, s96, -v185
	v_fma_f32 v63, v63, s96, -v185
	s_waitcnt lgkmcnt(5)
	v_mfma_f32_32x32x16_bf16 v[0:15], v[124:127], v[48:51], v[0:15]
	v_exp_f32_e32 v186, v32
	v_fma_f32 v32, v33, s96, -v185
	v_add_f32_e32 v152, v52, v152
	v_exp_f32_e32 v56, v56
	v_exp_f32_e32 v57, v57
	v_exp_f32_e32 v58, v58
	v_exp_f32_e32 v59, v59
	v_exp_f32_e32 v60, v60
	v_exp_f32_e32 v61, v61
	v_exp_f32_e32 v62, v62
	v_exp_f32_e32 v63, v63
	v_exp_f32_e32 v52, v32
	v_fma_f32 v32, v34, s96, -v185
	v_add_f32_e32 v152, v53, v152
	v_exp_f32_e32 v53, v32
	v_fma_f32 v32, v35, s96, -v185
	v_add_f32_e32 v152, v54, v152
	v_exp_f32_e32 v54, v32
	v_fma_f32 v32, v36, s96, -v185
	v_exp_f32_e32 v36, v32
	v_fma_f32 v32, v37, s96, -v185
	v_exp_f32_e32 v37, v32
	v_cvt_pk_bf16_f32 v32, v56, v57
	v_cvt_pk_bf16_f32 v33, v58, v59
	v_cvt_pk_bf16_f32 v34, v60, v61
	v_cvt_pk_bf16_f32 v35, v62, v63
	v_fma_f32 v38, v38, s96, -v185
	v_fma_f32 v39, v39, s96, -v185
	v_mfma_f32_32x32x16_bf16 v[16:31], v[120:123], v[32:35], v[16:31]
	v_exp_f32_e32 v38, v38
	v_exp_f32_e32 v39, v39
	v_add_f32_e32 v152, v55, v152
	v_add_f32_e32 v152, v56, v152
	v_add_f32_e32 v48, v57, v152
	v_fma_f32 v40, v40, s96, -v185
	v_fma_f32 v41, v41, s96, -v185
	s_waitcnt lgkmcnt(4)
	v_mfma_f32_32x32x16_bf16 v[0:15], v[116:119], v[32:35], v[0:15]
	v_fma_f32 v32, v42, s96, -v185
	v_exp_f32_e32 v42, v32
	v_cvt_pk_bf16_f32 v32, v186, v52
	v_cvt_pk_bf16_f32 v33, v53, v54
	v_cvt_pk_bf16_f32 v34, v36, v37
	v_cvt_pk_bf16_f32 v35, v38, v39
	v_fma_f32 v43, v43, s96, -v185
	v_fma_f32 v44, v44, s96, -v185
	s_waitcnt lgkmcnt(3)
	v_mfma_f32_32x32x16_bf16 v[16:31], v[112:115], v[32:35], v[16:31]
	v_fma_f32 v45, v45, s96, -v185
	v_fma_f32 v46, v46, s96, -v185
	v_add_f32_e32 v48, v58, v48
	v_exp_f32_e32 v40, v40
	v_exp_f32_e32 v41, v41
	v_exp_f32_e32 v43, v43
	v_exp_f32_e32 v44, v44
	s_waitcnt lgkmcnt(2)
	v_mfma_f32_32x32x16_bf16 v[0:15], v[108:111], v[32:35], v[0:15]
	v_fma_f32 v32, v47, s96, -v185
	v_exp_f32_e32 v45, v45
	v_exp_f32_e32 v46, v46
	v_exp_f32_e32 v47, v32
	v_add_f32_e32 v48, v59, v48
	v_add_f32_e32 v48, v60, v48
	v_add_f32_e32 v48, v61, v48
	v_add_f32_e32 v48, v62, v48
	v_cvt_pk_bf16_f32 v32, v40, v41
	v_cvt_pk_bf16_f32 v33, v42, v43
	v_cvt_pk_bf16_f32 v34, v44, v45
	v_cvt_pk_bf16_f32 v35, v46, v47
	v_add_f32_e32 v48, v63, v48
	s_mov_b64 s[4:5], 0x80
	s_waitcnt lgkmcnt(1)
	v_mfma_f32_32x32x16_bf16 v[16:31], v[104:107], v[32:35], v[16:31]
	s_add_i32 s6, s6, 1
	v_lshl_add_u64 v[144:145], v[144:145], 0, s[4:5]
	s_mov_b64 s[4:5], 0x3000
	v_lshl_add_u64 v[146:147], v[146:147], 0, s[4:5]
	s_cmp_eq_u32 s6, 19
	v_lshl_add_u64 v[148:149], v[148:149], 0, s[4:5]
	s_waitcnt lgkmcnt(0)
	v_mfma_f32_32x32x16_bf16 v[0:15], v[100:103], v[32:35], v[0:15]
	v_add_f32_e32 v32, v186, v48
	v_add_f32_e32 v32, v52, v32
	v_add_f32_e32 v32, v53, v32
	v_add_f32_e32 v32, v54, v32
	v_add_f32_e32 v32, v36, v32
	v_add_f32_e32 v32, v37, v32
	v_add_f32_e32 v32, v38, v32
	v_add_f32_e32 v32, v39, v32
	v_add_f32_e32 v32, v40, v32
	v_add_f32_e32 v32, v41, v32
	v_add_f32_e32 v32, v42, v32
	v_add_f32_e32 v32, v43, v32
	v_add_f32_e32 v32, v44, v32
	v_add_f32_e32 v32, v45, v32
	v_add_f32_e32 v32, v46, v32
	v_add_f32_e32 v152, v47, v32
	s_cbranch_scc0 .LBB0_610
	s_and_saveexec_b64 s[4:5], s[0:1]
	s_cbranch_execz .LBB0_624
	v_add_u32_e32 v32, v183, v184
	s_waitcnt vmcnt(1)
	ds_write_b128 v32, v[200:203] offset:13312
.LBB0_624:
	s_or_b64 exec, exec, s[4:5]
	s_and_saveexec_b64 s[0:1], s[36:37]
	s_cbranch_execz .LBB0_569
	v_add_u32_e32 v32, v181, v182
	s_waitcnt vmcnt(1)
	ds_write_b128 v32, v[204:207] offset:13312
	s_branch .LBB0_569
